# phase-5 group norm rewritten by hand: one wave per row with 16 channels per lane, all row loads issued up front, DPP quad reductions instead of ds_bpermute chains, v_cvt_pk_bf16 packing
# speedup vs baseline: 1.0499x; 1.0282x over previous
.LBB0_1350:
	s_cmp_lt_i32 s56, 6
	s_cselect_b64 s[4:5], -1, 0
	s_and_b64 s[4:5], s[4:5], s[0:1]
	s_andn2_b64 vcc, exec, s[4:5]
	v_lshrrev_b32_e32 v167, 6, v166
	s_cbranch_vccnz .LBB0_1355
	s_waitcnt vmcnt(0)
	v_lshl_add_u32 v2, s2, 3, v167
	s_mov_b32 s0, 0x20800
	v_cmp_gt_i32_e32 vcc, s0, v2
	s_and_saveexec_b64 s[6:7], vcc
	v_readlane_b32 s36, v239, 49
	v_readlane_b32 s38, v239, 51
	v_readlane_b32 s39, v239, 52
	v_readlane_b32 s40, v239, 53
	v_readlane_b32 s41, v239, 54
	v_readlane_b32 s37, v239, 50
	v_readlane_b32 s42, v239, 55
	v_readlane_b32 s43, v239, 56
	v_readlane_b32 s44, v239, 57
	v_readlane_b32 s45, v239, 58
	v_readlane_b32 s46, v239, 59
	v_readlane_b32 s47, v239, 60
	v_readlane_b32 s48, v239, 61
	v_readlane_b32 s49, v239, 62
	v_readlane_b32 s50, v239, 63
	v_readlane_b32 s51, v238, 0
	s_cbranch_execz .LBB0_1354
	v_and_b32_e32 v0, 63, v166
	v_mov_b32_e32 v3, 0x3a27c5ac
	v_lshlrev_b32_e32 v1, 5, v0
	v_lshlrev_b32_e32 v2, 6, v0
	v_readfirstlane_b32 s0, v167
	s_add_u32 s10, s94, 0x6a00000
	s_addc_u32 s11, s95, 0
	s_add_u32 s8, s94, 0x800000
	s_addc_u32 s9, s95, 0
	s_lshl_b32 s3, s2, 3
	s_add_i32 s3, s3, s0
	global_load_dwordx4 v[132:135], v2, s[38:39]
	global_load_dwordx4 v[136:139], v2, s[38:39] offset:16
	global_load_dwordx4 v[140:143], v2, s[38:39] offset:32
	global_load_dwordx4 v[144:147], v2, s[38:39] offset:48
	global_load_dwordx4 v[148:151], v2, s[40:41]
	global_load_dwordx4 v[152:155], v2, s[40:41] offset:16
	global_load_dwordx4 v[156:159], v2, s[40:41] offset:32
	global_load_dwordx4 v[160:163], v2, s[40:41] offset:48
	s_mov_b32 s12, s3
	s_lshl_b32 s13, s12, 12
	s_add_u32 s14, s10, s13
	s_addc_u32 s15, s11, 0
	s_lshl_b32 s13, s12, 11
	s_add_u32 s16, s92, s13
	s_addc_u32 s17, s93, 0
	s_add_u32 s0, s8, s13
	s_addc_u32 s1, s9, 0
	global_load_dwordx4 v[4:7], v1, s[14:15]
	global_load_dwordx4 v[8:11], v1, s[14:15] offset:16
	global_load_dwordx4 v[12:15], v1, s[16:17]
	global_load_dwordx4 v[16:19], v1, s[16:17] offset:16
	global_load_dwordx4 v[20:23], v1, s[0:1]
	global_load_dwordx4 v[24:27], v1, s[0:1] offset:16
	s_add_i32 s12, s3, 2048
	s_lshl_b32 s13, s12, 12
	s_add_u32 s14, s10, s13
	s_addc_u32 s15, s11, 0
	s_lshl_b32 s13, s12, 11
	s_add_u32 s16, s92, s13
	s_addc_u32 s17, s93, 0
	s_add_u32 s0, s8, s13
	s_addc_u32 s1, s9, 0
	global_load_dwordx4 v[28:31], v1, s[14:15]
	global_load_dwordx4 v[32:35], v1, s[14:15] offset:16
	global_load_dwordx4 v[36:39], v1, s[16:17]
	global_load_dwordx4 v[40:43], v1, s[16:17] offset:16
	global_load_dwordx4 v[44:47], v1, s[0:1]
	global_load_dwordx4 v[48:51], v1, s[0:1] offset:16
	s_add_i32 s12, s3, 4096
	s_lshl_b32 s13, s12, 12
	s_add_u32 s14, s10, s13
	s_addc_u32 s15, s11, 0
	s_lshl_b32 s13, s12, 11
	s_add_u32 s16, s92, s13
	s_addc_u32 s17, s93, 0
	s_add_u32 s0, s8, s13
	s_addc_u32 s1, s9, 0
	global_load_dwordx4 v[52:55], v1, s[14:15]
	global_load_dwordx4 v[56:59], v1, s[14:15] offset:16
	global_load_dwordx4 v[60:63], v1, s[16:17]
	global_load_dwordx4 v[64:67], v1, s[16:17] offset:16
	global_load_dwordx4 v[68:71], v1, s[0:1]
	global_load_dwordx4 v[72:75], v1, s[0:1] offset:16
	s_add_i32 s12, s3, 6144
	s_lshl_b32 s13, s12, 12
	s_add_u32 s14, s10, s13
	s_addc_u32 s15, s11, 0
	s_lshl_b32 s13, s12, 11
	s_add_u32 s16, s92, s13
	s_addc_u32 s17, s93, 0
	s_add_u32 s0, s8, s13
	s_addc_u32 s1, s9, 0
	global_load_dwordx4 v[76:79], v1, s[14:15]
	global_load_dwordx4 v[80:83], v1, s[14:15] offset:16
	global_load_dwordx4 v[84:87], v1, s[16:17]
	global_load_dwordx4 v[88:91], v1, s[16:17] offset:16
	global_load_dwordx4 v[92:95], v1, s[0:1]
	global_load_dwordx4 v[96:99], v1, s[0:1] offset:16
	s_add_i32 s12, s3, 0x2000
	s_cmpk_lt_i32 s12, 0x2080
	s_cselect_b32 s12, s12, s3
	s_lshl_b32 s13, s12, 12
	s_add_u32 s14, s10, s13
	s_addc_u32 s15, s11, 0
	s_lshl_b32 s13, s12, 11
	s_add_u32 s16, s92, s13
	s_addc_u32 s17, s93, 0
	s_add_u32 s0, s8, s13
	s_addc_u32 s1, s9, 0
	global_load_dwordx4 v[100:103], v1, s[14:15]
	global_load_dwordx4 v[104:107], v1, s[14:15] offset:16
	global_load_dwordx4 v[108:111], v1, s[16:17]
	global_load_dwordx4 v[112:115], v1, s[16:17] offset:16
	global_load_dwordx4 v[116:119], v1, s[0:1]
	global_load_dwordx4 v[120:123], v1, s[0:1] offset:16
	s_waitcnt vmcnt(24)
	v_lshlrev_b32_e32 v168, 16, v4
	v_and_b32_e32 v169, 0xffff0000, v4
	v_lshlrev_b32_e32 v170, 16, v5
	v_and_b32_e32 v171, 0xffff0000, v5
	v_lshlrev_b32_e32 v172, 16, v6
	v_and_b32_e32 v173, 0xffff0000, v6
	v_lshlrev_b32_e32 v174, 16, v7
	v_and_b32_e32 v175, 0xffff0000, v7
	v_lshlrev_b32_e32 v176, 16, v8
	v_and_b32_e32 v177, 0xffff0000, v8
	v_lshlrev_b32_e32 v178, 16, v9
	v_and_b32_e32 v179, 0xffff0000, v9
	v_lshlrev_b32_e32 v180, 16, v10
	v_and_b32_e32 v181, 0xffff0000, v10
	v_lshlrev_b32_e32 v182, 16, v11
	v_and_b32_e32 v183, 0xffff0000, v11
	v_pk_add_f32 v[184:185], v[168:169], v[170:171]
	v_pk_add_f32 v[186:187], v[172:173], v[174:175]
	v_pk_add_f32 v[188:189], v[176:177], v[178:179]
	v_pk_add_f32 v[190:191], v[180:181], v[182:183]
	v_pk_add_f32 v[184:185], v[184:185], v[186:187]
	v_pk_add_f32 v[188:189], v[188:189], v[190:191]
	v_pk_add_f32 v[184:185], v[184:185], v[188:189]
	v_add_f32_e32 v192, v184, v185
	s_nop 1
	v_add_f32_dpp v192, v192, v192 quad_perm:[1,0,3,2] row_mask:0xf bank_mask:0xf bound_ctrl:1
	s_nop 1
	v_add_f32_dpp v192, v192, v192 quad_perm:[2,3,0,1] row_mask:0xf bank_mask:0xf bound_ctrl:1
	v_mul_f32_e32 v194, 0x3c800000, v192
	v_pk_add_f32 v[168:169], v[168:169], v[194:195] op_sel_hi:[1,0] neg_lo:[0,1] neg_hi:[0,1]
	v_pk_add_f32 v[170:171], v[170:171], v[194:195] op_sel_hi:[1,0] neg_lo:[0,1] neg_hi:[0,1]
	v_pk_add_f32 v[172:173], v[172:173], v[194:195] op_sel_hi:[1,0] neg_lo:[0,1] neg_hi:[0,1]
	v_pk_add_f32 v[174:175], v[174:175], v[194:195] op_sel_hi:[1,0] neg_lo:[0,1] neg_hi:[0,1]
	v_pk_add_f32 v[176:177], v[176:177], v[194:195] op_sel_hi:[1,0] neg_lo:[0,1] neg_hi:[0,1]
	v_pk_add_f32 v[178:179], v[178:179], v[194:195] op_sel_hi:[1,0] neg_lo:[0,1] neg_hi:[0,1]
	v_pk_add_f32 v[180:181], v[180:181], v[194:195] op_sel_hi:[1,0] neg_lo:[0,1] neg_hi:[0,1]
	v_pk_add_f32 v[182:183], v[182:183], v[194:195] op_sel_hi:[1,0] neg_lo:[0,1] neg_hi:[0,1]
	v_pk_mul_f32 v[184:185], v[168:169], v[168:169]
	v_pk_mul_f32 v[186:187], v[170:171], v[170:171]
	v_pk_fma_f32 v[184:185], v[172:173], v[172:173], v[184:185]
	v_pk_fma_f32 v[186:187], v[174:175], v[174:175], v[186:187]
	v_pk_fma_f32 v[184:185], v[176:177], v[176:177], v[184:185]
	v_pk_fma_f32 v[186:187], v[178:179], v[178:179], v[186:187]
	v_pk_fma_f32 v[184:185], v[180:181], v[180:181], v[184:185]
	v_pk_fma_f32 v[186:187], v[182:183], v[182:183], v[186:187]
	v_pk_add_f32 v[184:185], v[184:185], v[186:187]
	v_add_f32_e32 v192, v184, v185
	s_nop 1
	v_add_f32_dpp v192, v192, v192 quad_perm:[1,0,3,2] row_mask:0xf bank_mask:0xf bound_ctrl:1
	s_nop 1
	v_add_f32_dpp v192, v192, v192 quad_perm:[2,3,0,1] row_mask:0xf bank_mask:0xf bound_ctrl:1
	v_fmamk_f32 v196, v192, 0x3c800000, v3
	v_rsq_f32_e32 v196, v196
	s_mov_b32 s12, s3
	s_lshl_b32 s13, s12, 12
	s_add_u32 s14, s10, s13
	s_addc_u32 s15, s11, 0
	v_pk_mul_f32 v[212:213], v[168:169], v[196:197] op_sel_hi:[1,0]
	v_lshlrev_b32_e32 v208, 16, v12
	v_and_b32_e32 v209, 0xffff0000, v12
	v_pk_fma_f32 v[212:213], v[212:213], v[132:133], v[148:149]
	v_lshlrev_b32_e32 v210, 16, v20
	v_and_b32_e32 v211, 0xffff0000, v20
	v_pk_add_f32 v[212:213], v[212:213], v[208:209]
	v_pk_mul_f32 v[212:213], v[212:213], v[210:211]
	v_cvt_pk_bf16_f32 v200, v212, v213
	v_pk_mul_f32 v[212:213], v[170:171], v[196:197] op_sel_hi:[1,0]
	v_lshlrev_b32_e32 v208, 16, v13
	v_and_b32_e32 v209, 0xffff0000, v13
	v_pk_fma_f32 v[212:213], v[212:213], v[134:135], v[150:151]
	v_lshlrev_b32_e32 v210, 16, v21
	v_and_b32_e32 v211, 0xffff0000, v21
	v_pk_add_f32 v[212:213], v[212:213], v[208:209]
	v_pk_mul_f32 v[212:213], v[212:213], v[210:211]
	v_cvt_pk_bf16_f32 v201, v212, v213
	v_pk_mul_f32 v[212:213], v[172:173], v[196:197] op_sel_hi:[1,0]
	v_lshlrev_b32_e32 v208, 16, v14
	v_and_b32_e32 v209, 0xffff0000, v14
	v_pk_fma_f32 v[212:213], v[212:213], v[136:137], v[152:153]
	v_lshlrev_b32_e32 v210, 16, v22
	v_and_b32_e32 v211, 0xffff0000, v22
	v_pk_add_f32 v[212:213], v[212:213], v[208:209]
	v_pk_mul_f32 v[212:213], v[212:213], v[210:211]
	v_cvt_pk_bf16_f32 v202, v212, v213
	v_pk_mul_f32 v[212:213], v[174:175], v[196:197] op_sel_hi:[1,0]
	v_lshlrev_b32_e32 v208, 16, v15
	v_and_b32_e32 v209, 0xffff0000, v15
	v_pk_fma_f32 v[212:213], v[212:213], v[138:139], v[154:155]
	v_lshlrev_b32_e32 v210, 16, v23
	v_and_b32_e32 v211, 0xffff0000, v23
	v_pk_add_f32 v[212:213], v[212:213], v[208:209]
	v_pk_mul_f32 v[212:213], v[212:213], v[210:211]
	v_cvt_pk_bf16_f32 v203, v212, v213
	v_pk_mul_f32 v[212:213], v[176:177], v[196:197] op_sel_hi:[1,0]
	v_lshlrev_b32_e32 v208, 16, v16
	v_and_b32_e32 v209, 0xffff0000, v16
	v_pk_fma_f32 v[212:213], v[212:213], v[140:141], v[156:157]
	v_lshlrev_b32_e32 v210, 16, v24
	v_and_b32_e32 v211, 0xffff0000, v24
	v_pk_add_f32 v[212:213], v[212:213], v[208:209]
	v_pk_mul_f32 v[212:213], v[212:213], v[210:211]
	v_cvt_pk_bf16_f32 v204, v212, v213
	v_pk_mul_f32 v[212:213], v[178:179], v[196:197] op_sel_hi:[1,0]
	v_lshlrev_b32_e32 v208, 16, v17
	v_and_b32_e32 v209, 0xffff0000, v17
	v_pk_fma_f32 v[212:213], v[212:213], v[142:143], v[158:159]
	v_lshlrev_b32_e32 v210, 16, v25
	v_and_b32_e32 v211, 0xffff0000, v25
	v_pk_add_f32 v[212:213], v[212:213], v[208:209]
	v_pk_mul_f32 v[212:213], v[212:213], v[210:211]
	v_cvt_pk_bf16_f32 v205, v212, v213
	v_pk_mul_f32 v[212:213], v[180:181], v[196:197] op_sel_hi:[1,0]
	v_lshlrev_b32_e32 v208, 16, v18
	v_and_b32_e32 v209, 0xffff0000, v18
	v_pk_fma_f32 v[212:213], v[212:213], v[144:145], v[160:161]
	v_lshlrev_b32_e32 v210, 16, v26
	v_and_b32_e32 v211, 0xffff0000, v26
	v_pk_add_f32 v[212:213], v[212:213], v[208:209]
	v_pk_mul_f32 v[212:213], v[212:213], v[210:211]
	v_cvt_pk_bf16_f32 v206, v212, v213
	v_pk_mul_f32 v[212:213], v[182:183], v[196:197] op_sel_hi:[1,0]
	v_lshlrev_b32_e32 v208, 16, v19
	v_and_b32_e32 v209, 0xffff0000, v19
	v_pk_fma_f32 v[212:213], v[212:213], v[146:147], v[162:163]
	v_lshlrev_b32_e32 v210, 16, v27
	v_and_b32_e32 v211, 0xffff0000, v27
	v_pk_add_f32 v[212:213], v[212:213], v[208:209]
	v_pk_mul_f32 v[212:213], v[212:213], v[210:211]
	v_cvt_pk_bf16_f32 v207, v212, v213
	global_store_dwordx4 v1, v[200:203], s[14:15]
	global_store_dwordx4 v1, v[204:207], s[14:15] offset:16
	s_waitcnt vmcnt(20)
	v_lshlrev_b32_e32 v168, 16, v28
	v_and_b32_e32 v169, 0xffff0000, v28
	v_lshlrev_b32_e32 v170, 16, v29
	v_and_b32_e32 v171, 0xffff0000, v29
	v_lshlrev_b32_e32 v172, 16, v30
	v_and_b32_e32 v173, 0xffff0000, v30
	v_lshlrev_b32_e32 v174, 16, v31
	v_and_b32_e32 v175, 0xffff0000, v31
	v_lshlrev_b32_e32 v176, 16, v32
	v_and_b32_e32 v177, 0xffff0000, v32
	v_lshlrev_b32_e32 v178, 16, v33
	v_and_b32_e32 v179, 0xffff0000, v33
	v_lshlrev_b32_e32 v180, 16, v34
	v_and_b32_e32 v181, 0xffff0000, v34
	v_lshlrev_b32_e32 v182, 16, v35
	v_and_b32_e32 v183, 0xffff0000, v35
	v_pk_add_f32 v[184:185], v[168:169], v[170:171]
	v_pk_add_f32 v[186:187], v[172:173], v[174:175]
	v_pk_add_f32 v[188:189], v[176:177], v[178:179]
	v_pk_add_f32 v[190:191], v[180:181], v[182:183]
	v_pk_add_f32 v[184:185], v[184:185], v[186:187]
	v_pk_add_f32 v[188:189], v[188:189], v[190:191]
	v_pk_add_f32 v[184:185], v[184:185], v[188:189]
	v_add_f32_e32 v192, v184, v185
	s_nop 1
	v_add_f32_dpp v192, v192, v192 quad_perm:[1,0,3,2] row_mask:0xf bank_mask:0xf bound_ctrl:1
	s_nop 1
	v_add_f32_dpp v192, v192, v192 quad_perm:[2,3,0,1] row_mask:0xf bank_mask:0xf bound_ctrl:1
	v_mul_f32_e32 v194, 0x3c800000, v192
	v_pk_add_f32 v[168:169], v[168:169], v[194:195] op_sel_hi:[1,0] neg_lo:[0,1] neg_hi:[0,1]
	v_pk_add_f32 v[170:171], v[170:171], v[194:195] op_sel_hi:[1,0] neg_lo:[0,1] neg_hi:[0,1]
	v_pk_add_f32 v[172:173], v[172:173], v[194:195] op_sel_hi:[1,0] neg_lo:[0,1] neg_hi:[0,1]
	v_pk_add_f32 v[174:175], v[174:175], v[194:195] op_sel_hi:[1,0] neg_lo:[0,1] neg_hi:[0,1]
	v_pk_add_f32 v[176:177], v[176:177], v[194:195] op_sel_hi:[1,0] neg_lo:[0,1] neg_hi:[0,1]
	v_pk_add_f32 v[178:179], v[178:179], v[194:195] op_sel_hi:[1,0] neg_lo:[0,1] neg_hi:[0,1]
	v_pk_add_f32 v[180:181], v[180:181], v[194:195] op_sel_hi:[1,0] neg_lo:[0,1] neg_hi:[0,1]
	v_pk_add_f32 v[182:183], v[182:183], v[194:195] op_sel_hi:[1,0] neg_lo:[0,1] neg_hi:[0,1]
	v_pk_mul_f32 v[184:185], v[168:169], v[168:169]
	v_pk_mul_f32 v[186:187], v[170:171], v[170:171]
	v_pk_fma_f32 v[184:185], v[172:173], v[172:173], v[184:185]
	v_pk_fma_f32 v[186:187], v[174:175], v[174:175], v[186:187]
	v_pk_fma_f32 v[184:185], v[176:177], v[176:177], v[184:185]
	v_pk_fma_f32 v[186:187], v[178:179], v[178:179], v[186:187]
	v_pk_fma_f32 v[184:185], v[180:181], v[180:181], v[184:185]
	v_pk_fma_f32 v[186:187], v[182:183], v[182:183], v[186:187]
	v_pk_add_f32 v[184:185], v[184:185], v[186:187]
	v_add_f32_e32 v192, v184, v185
	s_nop 1
	v_add_f32_dpp v192, v192, v192 quad_perm:[1,0,3,2] row_mask:0xf bank_mask:0xf bound_ctrl:1
	s_nop 1
	v_add_f32_dpp v192, v192, v192 quad_perm:[2,3,0,1] row_mask:0xf bank_mask:0xf bound_ctrl:1
	v_fmamk_f32 v196, v192, 0x3c800000, v3
	v_rsq_f32_e32 v196, v196
	s_add_i32 s12, s3, 2048
	s_lshl_b32 s13, s12, 12
	s_add_u32 s14, s10, s13
	s_addc_u32 s15, s11, 0
	v_pk_mul_f32 v[212:213], v[168:169], v[196:197] op_sel_hi:[1,0]
	v_lshlrev_b32_e32 v208, 16, v36
	v_and_b32_e32 v209, 0xffff0000, v36
	v_pk_fma_f32 v[212:213], v[212:213], v[132:133], v[148:149]
	v_lshlrev_b32_e32 v210, 16, v44
	v_and_b32_e32 v211, 0xffff0000, v44
	v_pk_add_f32 v[212:213], v[212:213], v[208:209]
	v_pk_mul_f32 v[212:213], v[212:213], v[210:211]
	v_cvt_pk_bf16_f32 v200, v212, v213
	v_pk_mul_f32 v[212:213], v[170:171], v[196:197] op_sel_hi:[1,0]
	v_lshlrev_b32_e32 v208, 16, v37
	v_and_b32_e32 v209, 0xffff0000, v37
	v_pk_fma_f32 v[212:213], v[212:213], v[134:135], v[150:151]
	v_lshlrev_b32_e32 v210, 16, v45
	v_and_b32_e32 v211, 0xffff0000, v45
	v_pk_add_f32 v[212:213], v[212:213], v[208:209]
	v_pk_mul_f32 v[212:213], v[212:213], v[210:211]
	v_cvt_pk_bf16_f32 v201, v212, v213
	v_pk_mul_f32 v[212:213], v[172:173], v[196:197] op_sel_hi:[1,0]
	v_lshlrev_b32_e32 v208, 16, v38
	v_and_b32_e32 v209, 0xffff0000, v38
	v_pk_fma_f32 v[212:213], v[212:213], v[136:137], v[152:153]
	v_lshlrev_b32_e32 v210, 16, v46
	v_and_b32_e32 v211, 0xffff0000, v46
	v_pk_add_f32 v[212:213], v[212:213], v[208:209]
	v_pk_mul_f32 v[212:213], v[212:213], v[210:211]
	v_cvt_pk_bf16_f32 v202, v212, v213
	v_pk_mul_f32 v[212:213], v[174:175], v[196:197] op_sel_hi:[1,0]
	v_lshlrev_b32_e32 v208, 16, v39
	v_and_b32_e32 v209, 0xffff0000, v39
	v_pk_fma_f32 v[212:213], v[212:213], v[138:139], v[154:155]
	v_lshlrev_b32_e32 v210, 16, v47
	v_and_b32_e32 v211, 0xffff0000, v47
	v_pk_add_f32 v[212:213], v[212:213], v[208:209]
	v_pk_mul_f32 v[212:213], v[212:213], v[210:211]
	v_cvt_pk_bf16_f32 v203, v212, v213
	v_pk_mul_f32 v[212:213], v[176:177], v[196:197] op_sel_hi:[1,0]
	v_lshlrev_b32_e32 v208, 16, v40
	v_and_b32_e32 v209, 0xffff0000, v40
	v_pk_fma_f32 v[212:213], v[212:213], v[140:141], v[156:157]
	v_lshlrev_b32_e32 v210, 16, v48
	v_and_b32_e32 v211, 0xffff0000, v48
	v_pk_add_f32 v[212:213], v[212:213], v[208:209]
	v_pk_mul_f32 v[212:213], v[212:213], v[210:211]
	v_cvt_pk_bf16_f32 v204, v212, v213
	v_pk_mul_f32 v[212:213], v[178:179], v[196:197] op_sel_hi:[1,0]
	v_lshlrev_b32_e32 v208, 16, v41
	v_and_b32_e32 v209, 0xffff0000, v41
	v_pk_fma_f32 v[212:213], v[212:213], v[142:143], v[158:159]
	v_lshlrev_b32_e32 v210, 16, v49
	v_and_b32_e32 v211, 0xffff0000, v49
	v_pk_add_f32 v[212:213], v[212:213], v[208:209]
	v_pk_mul_f32 v[212:213], v[212:213], v[210:211]
	v_cvt_pk_bf16_f32 v205, v212, v213
	v_pk_mul_f32 v[212:213], v[180:181], v[196:197] op_sel_hi:[1,0]
	v_lshlrev_b32_e32 v208, 16, v42
	v_and_b32_e32 v209, 0xffff0000, v42
	v_pk_fma_f32 v[212:213], v[212:213], v[144:145], v[160:161]
	v_lshlrev_b32_e32 v210, 16, v50
	v_and_b32_e32 v211, 0xffff0000, v50
	v_pk_add_f32 v[212:213], v[212:213], v[208:209]
	v_pk_mul_f32 v[212:213], v[212:213], v[210:211]
	v_cvt_pk_bf16_f32 v206, v212, v213
	v_pk_mul_f32 v[212:213], v[182:183], v[196:197] op_sel_hi:[1,0]
	v_lshlrev_b32_e32 v208, 16, v43
	v_and_b32_e32 v209, 0xffff0000, v43
	v_pk_fma_f32 v[212:213], v[212:213], v[146:147], v[162:163]
	v_lshlrev_b32_e32 v210, 16, v51
	v_and_b32_e32 v211, 0xffff0000, v51
	v_pk_add_f32 v[212:213], v[212:213], v[208:209]
	v_pk_mul_f32 v[212:213], v[212:213], v[210:211]
	v_cvt_pk_bf16_f32 v207, v212, v213
	global_store_dwordx4 v1, v[200:203], s[14:15]
	global_store_dwordx4 v1, v[204:207], s[14:15] offset:16
	s_waitcnt vmcnt(16)
	v_lshlrev_b32_e32 v168, 16, v52
	v_and_b32_e32 v169, 0xffff0000, v52
	v_lshlrev_b32_e32 v170, 16, v53
	v_and_b32_e32 v171, 0xffff0000, v53
	v_lshlrev_b32_e32 v172, 16, v54
	v_and_b32_e32 v173, 0xffff0000, v54
	v_lshlrev_b32_e32 v174, 16, v55
	v_and_b32_e32 v175, 0xffff0000, v55
	v_lshlrev_b32_e32 v176, 16, v56
	v_and_b32_e32 v177, 0xffff0000, v56
	v_lshlrev_b32_e32 v178, 16, v57
	v_and_b32_e32 v179, 0xffff0000, v57
	v_lshlrev_b32_e32 v180, 16, v58
	v_and_b32_e32 v181, 0xffff0000, v58
	v_lshlrev_b32_e32 v182, 16, v59
	v_and_b32_e32 v183, 0xffff0000, v59
	v_pk_add_f32 v[184:185], v[168:169], v[170:171]
	v_pk_add_f32 v[186:187], v[172:173], v[174:175]
	v_pk_add_f32 v[188:189], v[176:177], v[178:179]
	v_pk_add_f32 v[190:191], v[180:181], v[182:183]
	v_pk_add_f32 v[184:185], v[184:185], v[186:187]
	v_pk_add_f32 v[188:189], v[188:189], v[190:191]
	v_pk_add_f32 v[184:185], v[184:185], v[188:189]
	v_add_f32_e32 v192, v184, v185
	s_nop 1
	v_add_f32_dpp v192, v192, v192 quad_perm:[1,0,3,2] row_mask:0xf bank_mask:0xf bound_ctrl:1
	s_nop 1
	v_add_f32_dpp v192, v192, v192 quad_perm:[2,3,0,1] row_mask:0xf bank_mask:0xf bound_ctrl:1
	v_mul_f32_e32 v194, 0x3c800000, v192
	v_pk_add_f32 v[168:169], v[168:169], v[194:195] op_sel_hi:[1,0] neg_lo:[0,1] neg_hi:[0,1]
	v_pk_add_f32 v[170:171], v[170:171], v[194:195] op_sel_hi:[1,0] neg_lo:[0,1] neg_hi:[0,1]
	v_pk_add_f32 v[172:173], v[172:173], v[194:195] op_sel_hi:[1,0] neg_lo:[0,1] neg_hi:[0,1]
	v_pk_add_f32 v[174:175], v[174:175], v[194:195] op_sel_hi:[1,0] neg_lo:[0,1] neg_hi:[0,1]
	v_pk_add_f32 v[176:177], v[176:177], v[194:195] op_sel_hi:[1,0] neg_lo:[0,1] neg_hi:[0,1]
	v_pk_add_f32 v[178:179], v[178:179], v[194:195] op_sel_hi:[1,0] neg_lo:[0,1] neg_hi:[0,1]
	v_pk_add_f32 v[180:181], v[180:181], v[194:195] op_sel_hi:[1,0] neg_lo:[0,1] neg_hi:[0,1]
	v_pk_add_f32 v[182:183], v[182:183], v[194:195] op_sel_hi:[1,0] neg_lo:[0,1] neg_hi:[0,1]
	v_pk_mul_f32 v[184:185], v[168:169], v[168:169]
	v_pk_mul_f32 v[186:187], v[170:171], v[170:171]
	v_pk_fma_f32 v[184:185], v[172:173], v[172:173], v[184:185]
	v_pk_fma_f32 v[186:187], v[174:175], v[174:175], v[186:187]
	v_pk_fma_f32 v[184:185], v[176:177], v[176:177], v[184:185]
	v_pk_fma_f32 v[186:187], v[178:179], v[178:179], v[186:187]
	v_pk_fma_f32 v[184:185], v[180:181], v[180:181], v[184:185]
	v_pk_fma_f32 v[186:187], v[182:183], v[182:183], v[186:187]
	v_pk_add_f32 v[184:185], v[184:185], v[186:187]
	v_add_f32_e32 v192, v184, v185
	s_nop 1
	v_add_f32_dpp v192, v192, v192 quad_perm:[1,0,3,2] row_mask:0xf bank_mask:0xf bound_ctrl:1
	s_nop 1
	v_add_f32_dpp v192, v192, v192 quad_perm:[2,3,0,1] row_mask:0xf bank_mask:0xf bound_ctrl:1
	v_fmamk_f32 v196, v192, 0x3c800000, v3
	v_rsq_f32_e32 v196, v196
	s_add_i32 s12, s3, 4096
	s_lshl_b32 s13, s12, 12
	s_add_u32 s14, s10, s13
	s_addc_u32 s15, s11, 0
	v_pk_mul_f32 v[212:213], v[168:169], v[196:197] op_sel_hi:[1,0]
	v_lshlrev_b32_e32 v208, 16, v60
	v_and_b32_e32 v209, 0xffff0000, v60
	v_pk_fma_f32 v[212:213], v[212:213], v[132:133], v[148:149]
	v_lshlrev_b32_e32 v210, 16, v68
	v_and_b32_e32 v211, 0xffff0000, v68
	v_pk_add_f32 v[212:213], v[212:213], v[208:209]
	v_pk_mul_f32 v[212:213], v[212:213], v[210:211]
	v_cvt_pk_bf16_f32 v200, v212, v213
	v_pk_mul_f32 v[212:213], v[170:171], v[196:197] op_sel_hi:[1,0]
	v_lshlrev_b32_e32 v208, 16, v61
	v_and_b32_e32 v209, 0xffff0000, v61
	v_pk_fma_f32 v[212:213], v[212:213], v[134:135], v[150:151]
	v_lshlrev_b32_e32 v210, 16, v69
	v_and_b32_e32 v211, 0xffff0000, v69
	v_pk_add_f32 v[212:213], v[212:213], v[208:209]
	v_pk_mul_f32 v[212:213], v[212:213], v[210:211]
	v_cvt_pk_bf16_f32 v201, v212, v213
	v_pk_mul_f32 v[212:213], v[172:173], v[196:197] op_sel_hi:[1,0]
	v_lshlrev_b32_e32 v208, 16, v62
	v_and_b32_e32 v209, 0xffff0000, v62
	v_pk_fma_f32 v[212:213], v[212:213], v[136:137], v[152:153]
	v_lshlrev_b32_e32 v210, 16, v70
	v_and_b32_e32 v211, 0xffff0000, v70
	v_pk_add_f32 v[212:213], v[212:213], v[208:209]
	v_pk_mul_f32 v[212:213], v[212:213], v[210:211]
	v_cvt_pk_bf16_f32 v202, v212, v213
	v_pk_mul_f32 v[212:213], v[174:175], v[196:197] op_sel_hi:[1,0]
	v_lshlrev_b32_e32 v208, 16, v63
	v_and_b32_e32 v209, 0xffff0000, v63
	v_pk_fma_f32 v[212:213], v[212:213], v[138:139], v[154:155]
	v_lshlrev_b32_e32 v210, 16, v71
	v_and_b32_e32 v211, 0xffff0000, v71
	v_pk_add_f32 v[212:213], v[212:213], v[208:209]
	v_pk_mul_f32 v[212:213], v[212:213], v[210:211]
	v_cvt_pk_bf16_f32 v203, v212, v213
	v_pk_mul_f32 v[212:213], v[176:177], v[196:197] op_sel_hi:[1,0]
	v_lshlrev_b32_e32 v208, 16, v64
	v_and_b32_e32 v209, 0xffff0000, v64
	v_pk_fma_f32 v[212:213], v[212:213], v[140:141], v[156:157]
	v_lshlrev_b32_e32 v210, 16, v72
	v_and_b32_e32 v211, 0xffff0000, v72
	v_pk_add_f32 v[212:213], v[212:213], v[208:209]
	v_pk_mul_f32 v[212:213], v[212:213], v[210:211]
	v_cvt_pk_bf16_f32 v204, v212, v213
	v_pk_mul_f32 v[212:213], v[178:179], v[196:197] op_sel_hi:[1,0]
	v_lshlrev_b32_e32 v208, 16, v65
	v_and_b32_e32 v209, 0xffff0000, v65
	v_pk_fma_f32 v[212:213], v[212:213], v[142:143], v[158:159]
	v_lshlrev_b32_e32 v210, 16, v73
	v_and_b32_e32 v211, 0xffff0000, v73
	v_pk_add_f32 v[212:213], v[212:213], v[208:209]
	v_pk_mul_f32 v[212:213], v[212:213], v[210:211]
	v_cvt_pk_bf16_f32 v205, v212, v213
	v_pk_mul_f32 v[212:213], v[180:181], v[196:197] op_sel_hi:[1,0]
	v_lshlrev_b32_e32 v208, 16, v66
	v_and_b32_e32 v209, 0xffff0000, v66
	v_pk_fma_f32 v[212:213], v[212:213], v[144:145], v[160:161]
	v_lshlrev_b32_e32 v210, 16, v74
	v_and_b32_e32 v211, 0xffff0000, v74
	v_pk_add_f32 v[212:213], v[212:213], v[208:209]
	v_pk_mul_f32 v[212:213], v[212:213], v[210:211]
	v_cvt_pk_bf16_f32 v206, v212, v213
	v_pk_mul_f32 v[212:213], v[182:183], v[196:197] op_sel_hi:[1,0]
	v_lshlrev_b32_e32 v208, 16, v67
	v_and_b32_e32 v209, 0xffff0000, v67
	v_pk_fma_f32 v[212:213], v[212:213], v[146:147], v[162:163]
	v_lshlrev_b32_e32 v210, 16, v75
	v_and_b32_e32 v211, 0xffff0000, v75
	v_pk_add_f32 v[212:213], v[212:213], v[208:209]
	v_pk_mul_f32 v[212:213], v[212:213], v[210:211]
	v_cvt_pk_bf16_f32 v207, v212, v213
	global_store_dwordx4 v1, v[200:203], s[14:15]
	global_store_dwordx4 v1, v[204:207], s[14:15] offset:16
	s_waitcnt vmcnt(12)
	v_lshlrev_b32_e32 v168, 16, v76
	v_and_b32_e32 v169, 0xffff0000, v76
	v_lshlrev_b32_e32 v170, 16, v77
	v_and_b32_e32 v171, 0xffff0000, v77
	v_lshlrev_b32_e32 v172, 16, v78
	v_and_b32_e32 v173, 0xffff0000, v78
	v_lshlrev_b32_e32 v174, 16, v79
	v_and_b32_e32 v175, 0xffff0000, v79
	v_lshlrev_b32_e32 v176, 16, v80
	v_and_b32_e32 v177, 0xffff0000, v80
	v_lshlrev_b32_e32 v178, 16, v81
	v_and_b32_e32 v179, 0xffff0000, v81
	v_lshlrev_b32_e32 v180, 16, v82
	v_and_b32_e32 v181, 0xffff0000, v82
	v_lshlrev_b32_e32 v182, 16, v83
	v_and_b32_e32 v183, 0xffff0000, v83
	v_pk_add_f32 v[184:185], v[168:169], v[170:171]
	v_pk_add_f32 v[186:187], v[172:173], v[174:175]
	v_pk_add_f32 v[188:189], v[176:177], v[178:179]
	v_pk_add_f32 v[190:191], v[180:181], v[182:183]
	v_pk_add_f32 v[184:185], v[184:185], v[186:187]
	v_pk_add_f32 v[188:189], v[188:189], v[190:191]
	v_pk_add_f32 v[184:185], v[184:185], v[188:189]
	v_add_f32_e32 v192, v184, v185
	s_nop 1
	v_add_f32_dpp v192, v192, v192 quad_perm:[1,0,3,2] row_mask:0xf bank_mask:0xf bound_ctrl:1
	s_nop 1
	v_add_f32_dpp v192, v192, v192 quad_perm:[2,3,0,1] row_mask:0xf bank_mask:0xf bound_ctrl:1
	v_mul_f32_e32 v194, 0x3c800000, v192
	v_pk_add_f32 v[168:169], v[168:169], v[194:195] op_sel_hi:[1,0] neg_lo:[0,1] neg_hi:[0,1]
	v_pk_add_f32 v[170:171], v[170:171], v[194:195] op_sel_hi:[1,0] neg_lo:[0,1] neg_hi:[0,1]
	v_pk_add_f32 v[172:173], v[172:173], v[194:195] op_sel_hi:[1,0] neg_lo:[0,1] neg_hi:[0,1]
	v_pk_add_f32 v[174:175], v[174:175], v[194:195] op_sel_hi:[1,0] neg_lo:[0,1] neg_hi:[0,1]
	v_pk_add_f32 v[176:177], v[176:177], v[194:195] op_sel_hi:[1,0] neg_lo:[0,1] neg_hi:[0,1]
	v_pk_add_f32 v[178:179], v[178:179], v[194:195] op_sel_hi:[1,0] neg_lo:[0,1] neg_hi:[0,1]
	v_pk_add_f32 v[180:181], v[180:181], v[194:195] op_sel_hi:[1,0] neg_lo:[0,1] neg_hi:[0,1]
	v_pk_add_f32 v[182:183], v[182:183], v[194:195] op_sel_hi:[1,0] neg_lo:[0,1] neg_hi:[0,1]
	v_pk_mul_f32 v[184:185], v[168:169], v[168:169]
	v_pk_mul_f32 v[186:187], v[170:171], v[170:171]
	v_pk_fma_f32 v[184:185], v[172:173], v[172:173], v[184:185]
	v_pk_fma_f32 v[186:187], v[174:175], v[174:175], v[186:187]
	v_pk_fma_f32 v[184:185], v[176:177], v[176:177], v[184:185]
	v_pk_fma_f32 v[186:187], v[178:179], v[178:179], v[186:187]
	v_pk_fma_f32 v[184:185], v[180:181], v[180:181], v[184:185]
	v_pk_fma_f32 v[186:187], v[182:183], v[182:183], v[186:187]
	v_pk_add_f32 v[184:185], v[184:185], v[186:187]
	v_add_f32_e32 v192, v184, v185
	s_nop 1
	v_add_f32_dpp v192, v192, v192 quad_perm:[1,0,3,2] row_mask:0xf bank_mask:0xf bound_ctrl:1
	s_nop 1
	v_add_f32_dpp v192, v192, v192 quad_perm:[2,3,0,1] row_mask:0xf bank_mask:0xf bound_ctrl:1
	v_fmamk_f32 v196, v192, 0x3c800000, v3
	v_rsq_f32_e32 v196, v196
	s_add_i32 s12, s3, 6144
	s_lshl_b32 s13, s12, 12
	s_add_u32 s14, s10, s13
	s_addc_u32 s15, s11, 0
	v_pk_mul_f32 v[212:213], v[168:169], v[196:197] op_sel_hi:[1,0]
	v_lshlrev_b32_e32 v208, 16, v84
	v_and_b32_e32 v209, 0xffff0000, v84
	v_pk_fma_f32 v[212:213], v[212:213], v[132:133], v[148:149]
	v_lshlrev_b32_e32 v210, 16, v92
	v_and_b32_e32 v211, 0xffff0000, v92
	v_pk_add_f32 v[212:213], v[212:213], v[208:209]
	v_pk_mul_f32 v[212:213], v[212:213], v[210:211]
	v_cvt_pk_bf16_f32 v200, v212, v213
	v_pk_mul_f32 v[212:213], v[170:171], v[196:197] op_sel_hi:[1,0]
	v_lshlrev_b32_e32 v208, 16, v85
	v_and_b32_e32 v209, 0xffff0000, v85
	v_pk_fma_f32 v[212:213], v[212:213], v[134:135], v[150:151]
	v_lshlrev_b32_e32 v210, 16, v93
	v_and_b32_e32 v211, 0xffff0000, v93
	v_pk_add_f32 v[212:213], v[212:213], v[208:209]
	v_pk_mul_f32 v[212:213], v[212:213], v[210:211]
	v_cvt_pk_bf16_f32 v201, v212, v213
	v_pk_mul_f32 v[212:213], v[172:173], v[196:197] op_sel_hi:[1,0]
	v_lshlrev_b32_e32 v208, 16, v86
	v_and_b32_e32 v209, 0xffff0000, v86
	v_pk_fma_f32 v[212:213], v[212:213], v[136:137], v[152:153]
	v_lshlrev_b32_e32 v210, 16, v94
	v_and_b32_e32 v211, 0xffff0000, v94
	v_pk_add_f32 v[212:213], v[212:213], v[208:209]
	v_pk_mul_f32 v[212:213], v[212:213], v[210:211]
	v_cvt_pk_bf16_f32 v202, v212, v213
	v_pk_mul_f32 v[212:213], v[174:175], v[196:197] op_sel_hi:[1,0]
	v_lshlrev_b32_e32 v208, 16, v87
	v_and_b32_e32 v209, 0xffff0000, v87
	v_pk_fma_f32 v[212:213], v[212:213], v[138:139], v[154:155]
	v_lshlrev_b32_e32 v210, 16, v95
	v_and_b32_e32 v211, 0xffff0000, v95
	v_pk_add_f32 v[212:213], v[212:213], v[208:209]
	v_pk_mul_f32 v[212:213], v[212:213], v[210:211]
	v_cvt_pk_bf16_f32 v203, v212, v213
	v_pk_mul_f32 v[212:213], v[176:177], v[196:197] op_sel_hi:[1,0]
	v_lshlrev_b32_e32 v208, 16, v88
	v_and_b32_e32 v209, 0xffff0000, v88
	v_pk_fma_f32 v[212:213], v[212:213], v[140:141], v[156:157]
	v_lshlrev_b32_e32 v210, 16, v96
	v_and_b32_e32 v211, 0xffff0000, v96
	v_pk_add_f32 v[212:213], v[212:213], v[208:209]
	v_pk_mul_f32 v[212:213], v[212:213], v[210:211]
	v_cvt_pk_bf16_f32 v204, v212, v213
	v_pk_mul_f32 v[212:213], v[178:179], v[196:197] op_sel_hi:[1,0]
	v_lshlrev_b32_e32 v208, 16, v89
	v_and_b32_e32 v209, 0xffff0000, v89
	v_pk_fma_f32 v[212:213], v[212:213], v[142:143], v[158:159]
	v_lshlrev_b32_e32 v210, 16, v97
	v_and_b32_e32 v211, 0xffff0000, v97
	v_pk_add_f32 v[212:213], v[212:213], v[208:209]
	v_pk_mul_f32 v[212:213], v[212:213], v[210:211]
	v_cvt_pk_bf16_f32 v205, v212, v213
	v_pk_mul_f32 v[212:213], v[180:181], v[196:197] op_sel_hi:[1,0]
	v_lshlrev_b32_e32 v208, 16, v90
	v_and_b32_e32 v209, 0xffff0000, v90
	v_pk_fma_f32 v[212:213], v[212:213], v[144:145], v[160:161]
	v_lshlrev_b32_e32 v210, 16, v98
	v_and_b32_e32 v211, 0xffff0000, v98
	v_pk_add_f32 v[212:213], v[212:213], v[208:209]
	v_pk_mul_f32 v[212:213], v[212:213], v[210:211]
	v_cvt_pk_bf16_f32 v206, v212, v213
	v_pk_mul_f32 v[212:213], v[182:183], v[196:197] op_sel_hi:[1,0]
	v_lshlrev_b32_e32 v208, 16, v91
	v_and_b32_e32 v209, 0xffff0000, v91
	v_pk_fma_f32 v[212:213], v[212:213], v[146:147], v[162:163]
	v_lshlrev_b32_e32 v210, 16, v99
	v_and_b32_e32 v211, 0xffff0000, v99
	v_pk_add_f32 v[212:213], v[212:213], v[208:209]
	v_pk_mul_f32 v[212:213], v[212:213], v[210:211]
	v_cvt_pk_bf16_f32 v207, v212, v213
	global_store_dwordx4 v1, v[200:203], s[14:15]
	global_store_dwordx4 v1, v[204:207], s[14:15] offset:16
	s_add_i32 s12, s3, 0x2000
	s_cmpk_lt_i32 s12, 0x2080
	s_cbranch_scc0 .Lgn_done
	s_waitcnt vmcnt(8)
	v_lshlrev_b32_e32 v168, 16, v100
	v_and_b32_e32 v169, 0xffff0000, v100
	v_lshlrev_b32_e32 v170, 16, v101
	v_and_b32_e32 v171, 0xffff0000, v101
	v_lshlrev_b32_e32 v172, 16, v102
	v_and_b32_e32 v173, 0xffff0000, v102
	v_lshlrev_b32_e32 v174, 16, v103
	v_and_b32_e32 v175, 0xffff0000, v103
	v_lshlrev_b32_e32 v176, 16, v104
	v_and_b32_e32 v177, 0xffff0000, v104
	v_lshlrev_b32_e32 v178, 16, v105
	v_and_b32_e32 v179, 0xffff0000, v105
	v_lshlrev_b32_e32 v180, 16, v106
	v_and_b32_e32 v181, 0xffff0000, v106
	v_lshlrev_b32_e32 v182, 16, v107
	v_and_b32_e32 v183, 0xffff0000, v107
	v_pk_add_f32 v[184:185], v[168:169], v[170:171]
	v_pk_add_f32 v[186:187], v[172:173], v[174:175]
	v_pk_add_f32 v[188:189], v[176:177], v[178:179]
	v_pk_add_f32 v[190:191], v[180:181], v[182:183]
	v_pk_add_f32 v[184:185], v[184:185], v[186:187]
	v_pk_add_f32 v[188:189], v[188:189], v[190:191]
	v_pk_add_f32 v[184:185], v[184:185], v[188:189]
	v_add_f32_e32 v192, v184, v185
	s_nop 1
	v_add_f32_dpp v192, v192, v192 quad_perm:[1,0,3,2] row_mask:0xf bank_mask:0xf bound_ctrl:1
	s_nop 1
	v_add_f32_dpp v192, v192, v192 quad_perm:[2,3,0,1] row_mask:0xf bank_mask:0xf bound_ctrl:1
	v_mul_f32_e32 v194, 0x3c800000, v192
	v_pk_add_f32 v[168:169], v[168:169], v[194:195] op_sel_hi:[1,0] neg_lo:[0,1] neg_hi:[0,1]
	v_pk_add_f32 v[170:171], v[170:171], v[194:195] op_sel_hi:[1,0] neg_lo:[0,1] neg_hi:[0,1]
	v_pk_add_f32 v[172:173], v[172:173], v[194:195] op_sel_hi:[1,0] neg_lo:[0,1] neg_hi:[0,1]
	v_pk_add_f32 v[174:175], v[174:175], v[194:195] op_sel_hi:[1,0] neg_lo:[0,1] neg_hi:[0,1]
	v_pk_add_f32 v[176:177], v[176:177], v[194:195] op_sel_hi:[1,0] neg_lo:[0,1] neg_hi:[0,1]
	v_pk_add_f32 v[178:179], v[178:179], v[194:195] op_sel_hi:[1,0] neg_lo:[0,1] neg_hi:[0,1]
	v_pk_add_f32 v[180:181], v[180:181], v[194:195] op_sel_hi:[1,0] neg_lo:[0,1] neg_hi:[0,1]
	v_pk_add_f32 v[182:183], v[182:183], v[194:195] op_sel_hi:[1,0] neg_lo:[0,1] neg_hi:[0,1]
	v_pk_mul_f32 v[184:185], v[168:169], v[168:169]
	v_pk_mul_f32 v[186:187], v[170:171], v[170:171]
	v_pk_fma_f32 v[184:185], v[172:173], v[172:173], v[184:185]
	v_pk_fma_f32 v[186:187], v[174:175], v[174:175], v[186:187]
	v_pk_fma_f32 v[184:185], v[176:177], v[176:177], v[184:185]
	v_pk_fma_f32 v[186:187], v[178:179], v[178:179], v[186:187]
	v_pk_fma_f32 v[184:185], v[180:181], v[180:181], v[184:185]
	v_pk_fma_f32 v[186:187], v[182:183], v[182:183], v[186:187]
	v_pk_add_f32 v[184:185], v[184:185], v[186:187]
	v_add_f32_e32 v192, v184, v185
	s_nop 1
	v_add_f32_dpp v192, v192, v192 quad_perm:[1,0,3,2] row_mask:0xf bank_mask:0xf bound_ctrl:1
	s_nop 1
	v_add_f32_dpp v192, v192, v192 quad_perm:[2,3,0,1] row_mask:0xf bank_mask:0xf bound_ctrl:1
	v_fmamk_f32 v196, v192, 0x3c800000, v3
	v_rsq_f32_e32 v196, v196
	s_add_i32 s12, s3, 8192
	s_lshl_b32 s13, s12, 12
	s_add_u32 s14, s10, s13
	s_addc_u32 s15, s11, 0
	v_pk_mul_f32 v[212:213], v[168:169], v[196:197] op_sel_hi:[1,0]
	v_lshlrev_b32_e32 v208, 16, v108
	v_and_b32_e32 v209, 0xffff0000, v108
	v_pk_fma_f32 v[212:213], v[212:213], v[132:133], v[148:149]
	v_lshlrev_b32_e32 v210, 16, v116
	v_and_b32_e32 v211, 0xffff0000, v116
	v_pk_add_f32 v[212:213], v[212:213], v[208:209]
	v_pk_mul_f32 v[212:213], v[212:213], v[210:211]
	v_cvt_pk_bf16_f32 v200, v212, v213
	v_pk_mul_f32 v[212:213], v[170:171], v[196:197] op_sel_hi:[1,0]
	v_lshlrev_b32_e32 v208, 16, v109
	v_and_b32_e32 v209, 0xffff0000, v109
	v_pk_fma_f32 v[212:213], v[212:213], v[134:135], v[150:151]
	v_lshlrev_b32_e32 v210, 16, v117
	v_and_b32_e32 v211, 0xffff0000, v117
	v_pk_add_f32 v[212:213], v[212:213], v[208:209]
	v_pk_mul_f32 v[212:213], v[212:213], v[210:211]
	v_cvt_pk_bf16_f32 v201, v212, v213
	v_pk_mul_f32 v[212:213], v[172:173], v[196:197] op_sel_hi:[1,0]
	v_lshlrev_b32_e32 v208, 16, v110
	v_and_b32_e32 v209, 0xffff0000, v110
	v_pk_fma_f32 v[212:213], v[212:213], v[136:137], v[152:153]
	v_lshlrev_b32_e32 v210, 16, v118
	v_and_b32_e32 v211, 0xffff0000, v118
	v_pk_add_f32 v[212:213], v[212:213], v[208:209]
	v_pk_mul_f32 v[212:213], v[212:213], v[210:211]
	v_cvt_pk_bf16_f32 v202, v212, v213
	v_pk_mul_f32 v[212:213], v[174:175], v[196:197] op_sel_hi:[1,0]
	v_lshlrev_b32_e32 v208, 16, v111
	v_and_b32_e32 v209, 0xffff0000, v111
	v_pk_fma_f32 v[212:213], v[212:213], v[138:139], v[154:155]
	v_lshlrev_b32_e32 v210, 16, v119
	v_and_b32_e32 v211, 0xffff0000, v119
	v_pk_add_f32 v[212:213], v[212:213], v[208:209]
	v_pk_mul_f32 v[212:213], v[212:213], v[210:211]
	v_cvt_pk_bf16_f32 v203, v212, v213
	v_pk_mul_f32 v[212:213], v[176:177], v[196:197] op_sel_hi:[1,0]
	v_lshlrev_b32_e32 v208, 16, v112
	v_and_b32_e32 v209, 0xffff0000, v112
	v_pk_fma_f32 v[212:213], v[212:213], v[140:141], v[156:157]
	v_lshlrev_b32_e32 v210, 16, v120
	v_and_b32_e32 v211, 0xffff0000, v120
	v_pk_add_f32 v[212:213], v[212:213], v[208:209]
	v_pk_mul_f32 v[212:213], v[212:213], v[210:211]
	v_cvt_pk_bf16_f32 v204, v212, v213
	v_pk_mul_f32 v[212:213], v[178:179], v[196:197] op_sel_hi:[1,0]
	v_lshlrev_b32_e32 v208, 16, v113
	v_and_b32_e32 v209, 0xffff0000, v113
	v_pk_fma_f32 v[212:213], v[212:213], v[142:143], v[158:159]
	v_lshlrev_b32_e32 v210, 16, v121
	v_and_b32_e32 v211, 0xffff0000, v121
	v_pk_add_f32 v[212:213], v[212:213], v[208:209]
	v_pk_mul_f32 v[212:213], v[212:213], v[210:211]
	v_cvt_pk_bf16_f32 v205, v212, v213
	v_pk_mul_f32 v[212:213], v[180:181], v[196:197] op_sel_hi:[1,0]
	v_lshlrev_b32_e32 v208, 16, v114
	v_and_b32_e32 v209, 0xffff0000, v114
	v_pk_fma_f32 v[212:213], v[212:213], v[144:145], v[160:161]
	v_lshlrev_b32_e32 v210, 16, v122
	v_and_b32_e32 v211, 0xffff0000, v122
	v_pk_add_f32 v[212:213], v[212:213], v[208:209]
	v_pk_mul_f32 v[212:213], v[212:213], v[210:211]
	v_cvt_pk_bf16_f32 v206, v212, v213
	v_pk_mul_f32 v[212:213], v[182:183], v[196:197] op_sel_hi:[1,0]
	v_lshlrev_b32_e32 v208, 16, v115
	v_and_b32_e32 v209, 0xffff0000, v115
	v_pk_fma_f32 v[212:213], v[212:213], v[146:147], v[162:163]
	v_lshlrev_b32_e32 v210, 16, v123
	v_and_b32_e32 v211, 0xffff0000, v123
	v_pk_add_f32 v[212:213], v[212:213], v[208:209]
	v_pk_mul_f32 v[212:213], v[212:213], v[210:211]
	v_cvt_pk_bf16_f32 v207, v212, v213
	global_store_dwordx4 v1, v[200:203], s[14:15]
	global_store_dwordx4 v1, v[204:207], s[14:15] offset:16
.Lgn_done:
	s_waitcnt vmcnt(0)
.LBB0_1354:
	s_or_b64 exec, exec, s[6:7]
